# baseline (speedup 1.0000x reference)
; __global__ void __launch_bounds__(NTHR) fwd_megakernel(Params p) {
;     ...
;   run_phase<0>(p); grid.sync();
.Lfb1_poll:
	global_load_dword v1, v0, s[2:3] sc1
	s_waitcnt vmcnt(0)
	v_readfirstlane_b32 s4, v1
	s_nop 3
	s_cmpk_ge_u32 s4, 1
	s_cbranch_scc1 .Lfb1_done
	s_sleep 1
	s_add_u32 s6, s6, 1
	s_cmp_lt_u32 s6, 0x200000
	s_cbranch_scc1 .Lfb1_poll

; __global__ void __launch_bounds__(NTHR) fwd_megakernel(Params p) {
;     ...
;   run_phase<1>(p); grid.sync();
.Lfb2_poll:
	global_load_dword v1, v0, s[2:3] sc1
	s_waitcnt vmcnt(0)
	v_readfirstlane_b32 s4, v1
	s_nop 3
	s_cmpk_ge_u32 s4, 2
	s_cbranch_scc1 .Lfb2_done
	s_sleep 1
	s_add_u32 s6, s6, 1
	s_cmp_lt_u32 s6, 0x200000
	s_cbranch_scc1 .Lfb2_poll

; __global__ void __launch_bounds__(NTHR) fwd_megakernel(Params p) {
;     ...
;   run_phase<2>(p); grid.sync();
.Lfb3_poll:
	global_load_dword v1, v0, s[2:3] sc1
	s_waitcnt vmcnt(0)
	v_readfirstlane_b32 s4, v1
	s_nop 3
	s_cmpk_ge_u32 s4, 3
	s_cbranch_scc1 .Lfb3_done
	s_sleep 1
	s_add_u32 s6, s6, 1
	s_cmp_lt_u32 s6, 0x200000
	s_cbranch_scc1 .Lfb3_poll

; __global__ void __launch_bounds__(NTHR) fwd_megakernel(Params p) {
;     ...
;   run_phase<3>(p); grid.sync();
.Lfb4_poll:
	global_load_dword v1, v0, s[2:3] sc1
	s_waitcnt vmcnt(0)
	v_readfirstlane_b32 s4, v1
	s_nop 3
	s_cmpk_ge_u32 s4, 4
	s_cbranch_scc1 .Lfb4_done
	s_sleep 1
	s_add_u32 s6, s6, 1
	s_cmp_lt_u32 s6, 0x200000
	s_cbranch_scc1 .Lfb4_poll

; __global__ void __launch_bounds__(NTHR) fwd_megakernel(Params p) {
;     ...
;   run_phase<4>(p); grid.sync();
.Lfb5_poll:
	global_load_dword v1, v0, s[4:5] sc1
	s_waitcnt vmcnt(0)
	v_readfirstlane_b32 s6, v1
	s_nop 3
	s_cmpk_ge_u32 s6, 5
	s_cbranch_scc1 .Lfb5_done
	s_sleep 1
	s_add_u32 s8, s8, 1
	s_cmp_lt_u32 s8, 0x200000
	s_cbranch_scc1 .Lfb5_poll

; __global__ void __launch_bounds__(NTHR) fwd_megakernel(Params p) {
;     ...
;   run_phase<5>(p); grid.sync();
.Lfb6_poll:
	global_load_dword v1, v0, s[4:5] sc1
	s_waitcnt vmcnt(0)
	v_readfirstlane_b32 s6, v1
	s_nop 3
	s_cmpk_ge_u32 s6, 6
	s_cbranch_scc1 .Lfb6_done
	s_sleep 1
	s_add_u32 s8, s8, 1
	s_cmp_lt_u32 s8, 0x200000
	s_cbranch_scc1 .Lfb6_poll
